# first grid barrier: census of the 16 per-XCC residency counters read with 16 loads in flight instead of 16 serialized round trips
# speedup vs baseline: 1.0067x; 1.0067x over previous
.LBB0_25:
	s_mov_b32 s6, s13
	s_mov_b32 s7, s16
	global_load_dword v16, v2, s[6:7] sc1
	global_load_dword v17, v2, s[6:7] offset:256 sc1
	global_load_dword v18, v2, s[6:7] offset:512 sc1
	global_load_dword v19, v2, s[6:7] offset:768 sc1
	global_load_dword v20, v2, s[6:7] offset:1024 sc1
	global_load_dword v21, v2, s[6:7] offset:1280 sc1
	global_load_dword v22, v2, s[6:7] offset:1536 sc1
	global_load_dword v23, v2, s[6:7] offset:1792 sc1
	global_load_dword v24, v2, s[6:7] offset:2048 sc1
	global_load_dword v25, v2, s[6:7] offset:2304 sc1
	global_load_dword v26, v2, s[6:7] offset:2560 sc1
	global_load_dword v27, v2, s[6:7] offset:2816 sc1
	global_load_dword v28, v2, s[6:7] offset:3072 sc1
	global_load_dword v29, v2, s[6:7] offset:3328 sc1
	global_load_dword v30, v2, s[6:7] offset:3584 sc1
	global_load_dword v31, v2, s[6:7] offset:3840 sc1
	s_waitcnt vmcnt(0)
	v_cmp_ne_u32_e32 vcc, 0, v16
	s_cmp_lg_u64 vcc, 0
	s_addc_u32 s10, s10, 0
	v_add_u32_e32 v3, v16, v3
	s_cmp_eq_u32 s12, 0x0
	s_cselect_b64 vcc, -1, 0
	s_nop 3
	v_cndmask_b32_e32 v1, v1, v16, vcc
	v_cmp_ne_u32_e32 vcc, 0, v17
	s_cmp_lg_u64 vcc, 0
	s_addc_u32 s10, s10, 0
	v_add_u32_e32 v3, v17, v3
	s_cmp_eq_u32 s12, 0x100
	s_cselect_b64 vcc, -1, 0
	s_nop 3
	v_cndmask_b32_e32 v1, v1, v17, vcc
	v_cmp_ne_u32_e32 vcc, 0, v18
	s_cmp_lg_u64 vcc, 0
	s_addc_u32 s10, s10, 0
	v_add_u32_e32 v3, v18, v3
	s_cmp_eq_u32 s12, 0x200
	s_cselect_b64 vcc, -1, 0
	s_nop 3
	v_cndmask_b32_e32 v1, v1, v18, vcc
	v_cmp_ne_u32_e32 vcc, 0, v19
	s_cmp_lg_u64 vcc, 0
	s_addc_u32 s10, s10, 0
	v_add_u32_e32 v3, v19, v3
	s_cmp_eq_u32 s12, 0x300
	s_cselect_b64 vcc, -1, 0
	s_nop 3
	v_cndmask_b32_e32 v1, v1, v19, vcc
	v_cmp_ne_u32_e32 vcc, 0, v20
	s_cmp_lg_u64 vcc, 0
	s_addc_u32 s10, s10, 0
	v_add_u32_e32 v3, v20, v3
	s_cmp_eq_u32 s12, 0x400
	s_cselect_b64 vcc, -1, 0
	s_nop 3
	v_cndmask_b32_e32 v1, v1, v20, vcc
	v_cmp_ne_u32_e32 vcc, 0, v21
	s_cmp_lg_u64 vcc, 0
	s_addc_u32 s10, s10, 0
	v_add_u32_e32 v3, v21, v3
	s_cmp_eq_u32 s12, 0x500
	s_cselect_b64 vcc, -1, 0
	s_nop 3
	v_cndmask_b32_e32 v1, v1, v21, vcc
	v_cmp_ne_u32_e32 vcc, 0, v22
	s_cmp_lg_u64 vcc, 0
	s_addc_u32 s10, s10, 0
	v_add_u32_e32 v3, v22, v3
	s_cmp_eq_u32 s12, 0x600
	s_cselect_b64 vcc, -1, 0
	s_nop 3
	v_cndmask_b32_e32 v1, v1, v22, vcc
	v_cmp_ne_u32_e32 vcc, 0, v23
	s_cmp_lg_u64 vcc, 0
	s_addc_u32 s10, s10, 0
	v_add_u32_e32 v3, v23, v3
	s_cmp_eq_u32 s12, 0x700
	s_cselect_b64 vcc, -1, 0
	s_nop 3
	v_cndmask_b32_e32 v1, v1, v23, vcc
	v_cmp_ne_u32_e32 vcc, 0, v24
	s_cmp_lg_u64 vcc, 0
	s_addc_u32 s10, s10, 0
	v_add_u32_e32 v3, v24, v3
	s_cmp_eq_u32 s12, 0x800
	s_cselect_b64 vcc, -1, 0
	s_nop 3
	v_cndmask_b32_e32 v1, v1, v24, vcc
	v_cmp_ne_u32_e32 vcc, 0, v25
	s_cmp_lg_u64 vcc, 0
	s_addc_u32 s10, s10, 0
	v_add_u32_e32 v3, v25, v3
	s_cmp_eq_u32 s12, 0x900
	s_cselect_b64 vcc, -1, 0
	s_nop 3
	v_cndmask_b32_e32 v1, v1, v25, vcc
	v_cmp_ne_u32_e32 vcc, 0, v26
	s_cmp_lg_u64 vcc, 0
	s_addc_u32 s10, s10, 0
	v_add_u32_e32 v3, v26, v3
	s_cmp_eq_u32 s12, 0xa00
	s_cselect_b64 vcc, -1, 0
	s_nop 3
	v_cndmask_b32_e32 v1, v1, v26, vcc
	v_cmp_ne_u32_e32 vcc, 0, v27
	s_cmp_lg_u64 vcc, 0
	s_addc_u32 s10, s10, 0
	v_add_u32_e32 v3, v27, v3
	s_cmp_eq_u32 s12, 0xb00
	s_cselect_b64 vcc, -1, 0
	s_nop 3
	v_cndmask_b32_e32 v1, v1, v27, vcc
	v_cmp_ne_u32_e32 vcc, 0, v28
	s_cmp_lg_u64 vcc, 0
	s_addc_u32 s10, s10, 0
	v_add_u32_e32 v3, v28, v3
	s_cmp_eq_u32 s12, 0xc00
	s_cselect_b64 vcc, -1, 0
	s_nop 3
	v_cndmask_b32_e32 v1, v1, v28, vcc
	v_cmp_ne_u32_e32 vcc, 0, v29
	s_cmp_lg_u64 vcc, 0
	s_addc_u32 s10, s10, 0
	v_add_u32_e32 v3, v29, v3
	s_cmp_eq_u32 s12, 0xd00
	s_cselect_b64 vcc, -1, 0
	s_nop 3
	v_cndmask_b32_e32 v1, v1, v29, vcc
	v_cmp_ne_u32_e32 vcc, 0, v30
	s_cmp_lg_u64 vcc, 0
	s_addc_u32 s10, s10, 0
	v_add_u32_e32 v3, v30, v3
	s_cmp_eq_u32 s12, 0xe00
	s_cselect_b64 vcc, -1, 0
	s_nop 3
	v_cndmask_b32_e32 v1, v1, v30, vcc
	v_cmp_ne_u32_e32 vcc, 0, v31
	s_cmp_lg_u64 vcc, 0
	s_addc_u32 s10, s10, 0
	v_add_u32_e32 v3, v31, v3
	s_cmp_eq_u32 s12, 0xf00
	s_cselect_b64 vcc, -1, 0
	s_nop 3
	v_cndmask_b32_e32 v1, v1, v31, vcc
	v_mov_b32_e32 v4, v31
	v_cmp_ne_u32_e32 vcc, s17, v3
	s_mov_b64 s[4:5], -1
	s_mov_b64 s[6:7], -1
	s_cbranch_vccz .LBB0_23
	s_add_i32 s11, s11, 1
	s_and_b32 s6, s11, 0xff
	s_cmp_eq_u32 s6, 0
	s_cselect_b64 s[6:7], -1, 0
	s_and_b64 vcc, exec, s[6:7]
	s_sleep 1
	s_cbranch_vccz .LBB0_23
	global_load_dword v3, v2, s[14:15] offset:512 sc1
	s_waitcnt vmcnt(0)
	v_cmp_eq_u32_e32 vcc, 0, v3
	s_cbranch_vccz .LBB0_23
	s_cmp_gt_u32 s11, 0x40000
	s_mov_b64 s[4:5], 0
	s_cselect_b64 s[6:7], -1, 0
	s_branch .LBB0_23
